# v009 plus attention final epilogue staged through a private LDS tile: 8 dwordx4 stores per lane instead of 64 short stores
# baseline (speedup 1.0000x reference)
; __device__ __forceinline__ int crow(int r, int hi) { return (r & 3) + 8 * (r >> 2) + 4 * hi; }
; __device__ void attn_phase(const Params& p, int l, int L, unsigned char* smem, int T) {
;     ...
;       } else {
;         const float* sw = p.subln + l * 128;
;         const float sw0 = sw[r32], sw1 = sw[32 + r32], sw2 = sw[64 + r32], sw3 = sw[96 + r32];
;         bf16_t* Ow = AB + (rowbase + (size_t)qb * 256) * 1024 + 512 + h * 128 + (unsigned)((t3 >> 6) * 32 * 1024 + (t3 & 31));
; #pragma unroll
;         for (int r4 = 0; r4 < 4; ++r4) { const f32x4 a0 = OS[r4 * 512], a1 = OS[(4 + r4) * 512], a2 = OS[(8 + r4) * 512], a3 = OS[(12 + r4) * 512];
; #pragma unroll
;           for (int q = 0; q < 4; ++q) { const int r = r4 * 4 + q; const int orow = crow(r, hi);
;             const float i2 = lam * __builtin_amdgcn_rcpf(li1[orow]);
;             const float v0 = a0[q] - o[0][r] * i2, v1 = a1[q] - o[1][r] * i2, v2 = a2[q] - o[2][r] * i2, v3 = a3[q] - o[3][r] * i2;
;             float ss = v0 * v0 + v1 * v1 + v2 * v2 + v3 * v3;
;             ss += __shfl_xor(ss, 1, 64); ss += __shfl_xor(ss, 2, 64); ss += __shfl_xor(ss, 4, 64); ss += __shfl_xor(ss, 8, 64); ss += __shfl_xor(ss, 16, 64);
;             const float rs = rsqrtf(ss * (1.f / 128.f) + EPS) * oml;
.LBB0_195:
	v_lshrrev_b32_e32 v221, 6, v170
	v_cmp_lt_u32_e32 vcc, 3, v221
	v_mov_b32_e32 v222, 0x9000
	v_cndmask_b32_e32 v222, 0, v222, vcc
	v_lshl_add_u32 v222, v221, 13, v222
	v_add_u32_e32 v224, 0x4000, v222
	v_and_b32_e32 v222, 31, v170
	v_bfe_u32 v223, v170, 5, 1
	v_lshlrev_b32_e32 v222, 1, v222
	v_lshl_or_b32 v222, v223, 10, v222
	v_add_u32_e32 v220, v224, v222
	v_and_b32_e32 v225, 63, v170
	v_lshl_add_u32 v226, v225, 4, v224
	v_lshrrev_b32_e32 v222, 4, v225
	v_and_b32_e32 v223, 15, v225
	v_lshlrev_b32_e32 v222, 11, v222
	v_lshl_or_b32 v222, v223, 4, v222
	v_lshl_or_b32 v246, v221, 16, v222
	v_mov_b32_e32 v247, 0
	v_lshl_add_u64 v[244:245], s[16:17], 0, v[246:247]
	v_mov_b32_e32 v246, 0x2000
	v_lshlrev_b32_e32 v82, 9, v0
	v_and_b32_e32 v0, 31, v0
	s_movk_i32 s0, 0x8000
	v_and_or_b32 v0, v82, s0, v0
	v_cmp_lt_i32_e32 vcc, v183, v177
	v_lshl_add_u64 v[104:105], v[0:1], 1, s[16:17]
	s_mov_b32 s0, 0x10000
	v_cndmask_b32_e32 v0, v176, v183, vcc
	v_cmp_lt_i32_e32 vcc, v182, v177
	v_lshlrev_b32_e32 v197, 2, v0
	global_load_dword v112, v[154:155], off
	global_load_dword v111, v[154:155], off offset:128
	global_load_dword v110, v[154:155], off offset:256
	global_load_dword v109, v[154:155], off offset:384
	v_cndmask_b32_e32 v0, v176, v182, vcc
	v_cmp_lt_i32_e32 vcc, v181, v177
	v_lshlrev_b32_e32 v196, 2, v0
	global_load_dwordx4 v[82:85], v[102:103], off
	v_cndmask_b32_e32 v0, v176, v181, vcc
	v_cmp_lt_i32_e32 vcc, v180, v177
	v_lshlrev_b32_e32 v195, 2, v0
	ds_read_b128 v[98:101], v108
	v_cndmask_b32_e32 v0, v176, v180, vcc
	v_cmp_lt_i32_e32 vcc, v179, v177
	v_lshlrev_b32_e32 v113, 2, v0
	v_mov_b32_e32 v106, v50
	v_cndmask_b32_e32 v0, v176, v179, vcc
	v_add_co_u32_e32 v86, vcc, s33, v102
	s_waitcnt lgkmcnt(0)
	v_rcp_f32_e32 v98, v98
	v_addc_co_u32_e32 v87, vcc, 0, v103, vcc
	global_load_dwordx4 v[90:93], v[86:87], off
	v_add_co_u32_e32 v86, vcc, s0, v102
	v_mul_f32_e32 v98, v167, v98
	s_nop 0
	v_addc_co_u32_e32 v87, vcc, 0, v103, vcc
	v_add_co_u32_e32 v94, vcc, s66, v102
	global_load_dwordx4 v[86:89], v[86:87], off
	s_nop 0
	v_addc_co_u32_e32 v95, vcc, 0, v103, vcc
	global_load_dwordx4 v[94:97], v[94:95], off
	v_mov_b32_e32 v107, v34
	v_mov_b32_e32 v200, v2
	v_mov_b32_e32 v201, v18
	v_mov_b32_e32 v206, v3
	v_mov_b32_e32 v207, v19
	v_lshlrev_b32_e32 v0, 2, v0
	s_mov_b32 s0, 0x358637bd
	v_mov_b32_e32 v208, v7
	v_mov_b32_e32 v209, v23
	s_waitcnt vmcnt(3)
	v_mov_b32_e32 v198, v82
	v_rcp_f32_e32 v82, v99
	s_waitcnt vmcnt(2)
	v_mov_b32_e32 v199, v90
	v_pk_fma_f32 v[198:199], v[106:107], v[98:99], v[198:199] op_sel_hi:[1,0,1] neg_lo:[1,0,0] neg_hi:[1,0,0]
	v_mul_f32_e32 v82, v167, v82
	v_mov_b32_e32 v90, v83
	v_pk_mul_f32 v[106:107], v[198:199], v[198:199]
	s_waitcnt vmcnt(1)
	v_mov_b32_e32 v203, v86
	s_waitcnt vmcnt(0)
	v_mov_b32_e32 v202, v94
	v_pk_fma_f32 v[200:201], v[200:201], v[98:99], v[202:203] op_sel_hi:[1,0,1] neg_lo:[1,0,0] neg_hi:[1,0,0]
	v_mov_b32_e32 v98, v51
	v_mov_b32_e32 v99, v35
	v_pk_fma_f32 v[90:91], v[98:99], v[82:83], v[90:91] op_sel_hi:[1,0,1] neg_lo:[1,0,0] neg_hi:[1,0,0]
	v_mov_b32_e32 v86, v95
	v_pk_mul_f32 v[98:99], v[90:91], v[90:91]
	v_pk_fma_f32 v[82:83], v[206:207], v[82:83], v[86:87] op_sel_hi:[1,0,1] neg_lo:[1,0,0] neg_hi:[1,0,0]
	v_pk_mul_f32 v[202:203], v[200:201], v[200:201]
	v_pk_mul_f32 v[86:87], v[82:83], v[82:83]
	v_mov_b32_e32 v94, v98
	v_mov_b32_e32 v95, v106
	v_mov_b32_e32 v106, v99
	v_pk_add_f32 v[94:95], v[94:95], v[106:107]
	v_mov_b32_e32 v98, v87
	v_mov_b32_e32 v99, v203
	v_pk_add_f32 v[94:95], v[98:99], v[94:95]
	v_mov_b32_e32 v87, v202
	v_pk_add_f32 v[86:87], v[86:87], v[94:95]
	ds_bpermute_b32 v95, v197, v87
	ds_bpermute_b32 v94, v197, v86
	v_mov_b64_e32 v[106:107], s[0:1]
	v_mov_b32_e32 v98, v96
	v_mov_b32_e32 v99, v88
	v_mov_b32_e32 v88, v97
	s_waitcnt lgkmcnt(0)
	v_pk_add_f32 v[86:87], v[86:87], v[94:95]
	ds_bpermute_b32 v95, v196, v87
	ds_bpermute_b32 v94, v196, v86
	v_mov_b32_e32 v202, v6
	v_mov_b32_e32 v203, v22
	s_waitcnt lgkmcnt(0)
	v_pk_add_f32 v[86:87], v[86:87], v[94:95]
	ds_bpermute_b32 v95, v195, v87
	ds_bpermute_b32 v94, v195, v86
	s_waitcnt lgkmcnt(0)
	v_pk_add_f32 v[86:87], v[86:87], v[94:95]
	ds_bpermute_b32 v95, v113, v87
	ds_bpermute_b32 v94, v113, v86
	s_waitcnt lgkmcnt(0)
	v_pk_add_f32 v[86:87], v[86:87], v[94:95]
	ds_bpermute_b32 v95, v0, v87
	ds_bpermute_b32 v94, v0, v86
	s_waitcnt lgkmcnt(0)
; __device__ __forceinline__ unsigned short f2bf(float f) { return (unsigned short)(cvtpk(f, 0.f) & 0xffffu); }
; __device__ __forceinline__ int crow(int r, int hi) { return (r & 3) + 8 * (r >> 2) + 4 * hi; }
; __device__ void attn_phase(const Params& p, int l, int L, unsigned char* smem, int T) {
;     ...
;         for (int r4 = 0; r4 < 4; ++r4) { const f32x4 a0 = OS[r4 * 512], a1 = OS[(4 + r4) * 512], a2 = OS[(8 + r4) * 512], a3 = OS[(12 + r4) * 512];
; #pragma unroll
;           for (int q = 0; q < 4; ++q) { const int r = r4 * 4 + q; const int orow = crow(r, hi);
;             const float i2 = lam * __builtin_amdgcn_rcpf(li1[orow]);
;             const float v0 = a0[q] - o[0][r] * i2, v1 = a1[q] - o[1][r] * i2, v2 = a2[q] - o[2][r] * i2, v3 = a3[q] - o[3][r] * i2;
;             float ss = v0 * v0 + v1 * v1 + v2 * v2 + v3 * v3;
;             ss += __shfl_xor(ss, 1, 64); ss += __shfl_xor(ss, 2, 64); ss += __shfl_xor(ss, 4, 64); ss += __shfl_xor(ss, 8, 64); ss += __shfl_xor(ss, 16, 64);
;             const float rs = rsqrtf(ss * (1.f / 128.f) + EPS) * oml;
;             bf16_t* op = Ow + (size_t)orow * 1024;
;             op[0] = f2bf(v0 * rs * sw0); op[32] = f2bf(v1 * rs * sw1); op[64] = f2bf(v2 * rs * sw2); op[96] = f2bf(v3 * rs * sw3); } }
	v_pk_add_f32 v[86:87], v[86:87], v[94:95]
	s_nop 0
	v_pk_fma_f32 v[86:87], v[86:87], s[64:65], v[106:107] op_sel_hi:[1,0,0]
	v_mov_b32_e32 v95, v20
	v_mul_f32_e32 v94, 0x4b800000, v87
	v_cmp_gt_f32_e64 s[0:1], s63, v87
	v_cmp_gt_f32_e32 vcc, s63, v86
	s_nop 0
	v_cndmask_b32_e64 v87, v87, v94, s[0:1]
	v_rsq_f32_e32 v87, v87
	s_nop 0
	v_mul_f32_e32 v94, 0x45800000, v87
	v_cndmask_b32_e64 v87, v87, v94, s[0:1]
	v_mul_f32_e32 v87, v166, v87
	v_mul_f32_e32 v94, v198, v87
	v_mul_f32_e32 v94, v112, v94
	v_cvt_pk_bf16_f32 v94, v94, s0
	ds_write_b16 v220, v94 offset:0
	v_mul_f32_e32 v94, v199, v87
	v_mul_f32_e32 v94, v111, v94
	v_cvt_pk_bf16_f32 v94, v94, s0
	ds_write_b16 v220, v94 offset:64
	v_mul_f32_e32 v94, v201, v87
	v_mul_f32_e32 v87, v200, v87
	v_mul_f32_e32 v87, v109, v87
	v_cvt_pk_bf16_f32 v87, v87, s0
	ds_write_b16 v220, v87 offset:192
	v_mul_f32_e32 v87, 0x4b800000, v86
	v_cndmask_b32_e32 v86, v86, v87, vcc
	v_rsq_f32_e32 v86, v86
	v_mul_f32_e32 v94, v110, v94
	v_cvt_pk_bf16_f32 v94, v94, s0
	ds_write_b16 v220, v94 offset:128
	v_mul_f32_e32 v87, 0x45800000, v86
	v_cndmask_b32_e32 v86, v86, v87, vcc
	v_mul_f32_e32 v94, v166, v86
	v_mul_f32_e32 v90, v90, v94
	v_mul_f32_e32 v90, v112, v90
	v_cvt_pk_bf16_f32 v90, v90, s0
	ds_write_b16 v220, v90 offset:256
	v_mul_f32_e32 v90, v91, v94
	v_mul_f32_e32 v82, v82, v94
	v_mul_f32_e32 v90, v111, v90
	v_mul_f32_e32 v82, v109, v82
	v_cvt_pk_bf16_f32 v90, v90, s0
	v_cvt_pk_bf16_f32 v82, v82, s0
	ds_write_b16 v220, v90 offset:320
	ds_write_b16 v220, v82 offset:448
	v_rcp_f32_e32 v82, v100
	v_mov_b32_e32 v90, v84
	v_rcp_f32_e32 v84, v101
	v_mul_f32_e32 v83, v83, v94
	v_mul_f32_e32 v83, v110, v83
	v_cvt_pk_bf16_f32 v83, v83, s0
	ds_write_b16 v220, v83 offset:384
	v_mul_f32_e32 v82, v167, v82
	v_mov_b32_e32 v86, v52
	v_mov_b32_e32 v87, v36
	v_mov_b32_e32 v91, v92
	v_mul_f32_e32 v84, v167, v84
	v_mov_b32_e32 v100, v53
	v_mov_b32_e32 v101, v37
	v_mov_b32_e32 v92, v85
	v_pk_fma_f32 v[86:87], v[86:87], v[82:83], v[90:91] op_sel_hi:[1,0,1] neg_lo:[1,0,0] neg_hi:[1,0,0]
	v_mov_b32_e32 v94, v4
	v_pk_fma_f32 v[92:93], v[100:101], v[84:85], v[92:93] op_sel_hi:[1,0,1] neg_lo:[1,0,0] neg_hi:[1,0,0]
	v_mov_b32_e32 v198, v5
	v_mov_b32_e32 v199, v21
	v_pk_mul_f32 v[90:91], v[86:87], v[86:87]
	v_pk_fma_f32 v[82:83], v[94:95], v[82:83], v[98:99] op_sel_hi:[1,0,1] neg_lo:[1,0,0] neg_hi:[1,0,0]
	v_pk_mul_f32 v[100:101], v[92:93], v[92:93]
	v_pk_fma_f32 v[84:85], v[198:199], v[84:85], v[88:89] op_sel_hi:[1,0,1] neg_lo:[1,0,0] neg_hi:[1,0,0]
	v_pk_mul_f32 v[94:95], v[82:83], v[82:83]
	v_pk_mul_f32 v[88:89], v[84:85], v[84:85]
	v_mov_b32_e32 v96, v100
	v_mov_b32_e32 v97, v90
	v_mov_b32_e32 v90, v101
	v_pk_add_f32 v[90:91], v[96:97], v[90:91]
	v_mov_b32_e32 v96, v89
	v_mov_b32_e32 v97, v95
	v_pk_add_f32 v[90:91], v[96:97], v[90:91]
	v_mov_b32_e32 v89, v94
	v_pk_add_f32 v[88:89], v[88:89], v[90:91]
	ds_bpermute_b32 v91, v197, v89
	ds_bpermute_b32 v90, v197, v88
	v_mov_b32_e32 v198, v54
	v_mov_b32_e32 v199, v38
	s_waitcnt lgkmcnt(0)
	v_pk_add_f32 v[88:89], v[88:89], v[90:91]
	ds_bpermute_b32 v91, v196, v89
	ds_bpermute_b32 v90, v196, v88
	s_waitcnt lgkmcnt(0)
	v_pk_add_f32 v[88:89], v[88:89], v[90:91]
	ds_bpermute_b32 v91, v195, v89
	ds_bpermute_b32 v90, v195, v88
	s_waitcnt lgkmcnt(0)
	v_pk_add_f32 v[88:89], v[88:89], v[90:91]
	ds_bpermute_b32 v91, v113, v89
	ds_bpermute_b32 v90, v113, v88
	s_waitcnt lgkmcnt(0)
	v_pk_add_f32 v[88:89], v[88:89], v[90:91]
	ds_bpermute_b32 v91, v0, v89
	ds_bpermute_b32 v90, v0, v88
	s_waitcnt lgkmcnt(0)
	v_pk_add_f32 v[88:89], v[88:89], v[90:91]
	s_nop 0
	v_pk_fma_f32 v[88:89], v[88:89], s[64:65], v[106:107] op_sel_hi:[1,0,0]
	s_nop 0
	v_mul_f32_e32 v90, 0x4b800000, v89
	v_cmp_gt_f32_e64 s[0:1], s63, v89
	v_cmp_gt_f32_e32 vcc, s63, v88
	s_nop 0
	v_cndmask_b32_e64 v89, v89, v90, s[0:1]
	v_rsq_f32_e32 v89, v89
	s_nop 0
	v_mul_f32_e32 v90, 0x45800000, v89
	v_cndmask_b32_e64 v89, v89, v90, s[0:1]
	v_mul_f32_e32 v89, v166, v89
	v_mul_f32_e32 v82, v82, v89
	v_mul_f32_e32 v82, v109, v82
	v_cvt_pk_bf16_f32 v82, v82, s0
	ds_write_b16 v220, v82 offset:704
	v_mul_f32_e32 v82, 0x4b800000, v88
	v_cndmask_b32_e32 v82, v88, v82, vcc
	v_mul_f32_e32 v86, v86, v89
	v_rsq_f32_e32 v82, v82
	v_mul_f32_e32 v86, v112, v86
	v_mul_f32_e32 v83, v83, v89
	v_cvt_pk_bf16_f32 v86, v86, s0
	v_mul_f32_e32 v83, v110, v83
	ds_write_b16 v220, v86 offset:512
	v_mul_f32_e32 v86, v87, v89
	v_cvt_pk_bf16_f32 v83, v83, s0
	v_mul_f32_e32 v86, v111, v86
	ds_write_b16 v220, v83 offset:640
	v_mul_f32_e32 v83, 0x45800000, v82
	v_cvt_pk_bf16_f32 v86, v86, s0
	v_cndmask_b32_e32 v82, v82, v83, vcc
	ds_write_b16 v220, v86 offset:576
	v_mul_f32_e32 v86, v166, v82
	v_mul_f32_e32 v87, v92, v86
	v_mul_f32_e32 v87, v112, v87
	v_cvt_pk_bf16_f32 v87, v87, s0
	ds_write_b16 v220, v87 offset:768
	v_mul_f32_e32 v87, v93, v86
	v_mul_f32_e32 v85, v85, v86
	v_mul_f32_e32 v84, v84, v86
	v_mul_f32_e32 v87, v111, v87
	v_mul_f32_e32 v85, v110, v85
	v_mul_f32_e32 v84, v109, v84
	v_cvt_pk_bf16_f32 v87, v87, s0
	v_cvt_pk_bf16_f32 v85, v85, s0
	v_cvt_pk_bf16_f32 v84, v84, s0
	s_movk_i32 s0, 0x2000
	ds_write_b16 v220, v87 offset:832
	ds_write_b16 v220, v85 offset:896
	ds_write_b16 v220, v84 offset:960
	v_add_co_u32_e32 v82, vcc, s0, v102
	s_mov_b32 s0, 0xa000
	s_nop 0
	v_addc_co_u32_e32 v83, vcc, 0, v103, vcc
	global_load_dwordx4 v[86:89], v[82:83], off
	v_add_co_u32_e32 v82, vcc, s0, v102
	s_mov_b32 s0, 0x12000
	s_nop 0
	v_addc_co_u32_e32 v83, vcc, 0, v103, vcc
	global_load_dwordx4 v[90:93], v[82:83], off
	v_add_co_u32_e32 v82, vcc, s0, v102
	s_mov_b32 s0, 0x1a000
	s_nop 0
	v_addc_co_u32_e32 v83, vcc, 0, v103, vcc
	global_load_dwordx4 v[82:85], v[82:83], off
	v_add_co_u32_e32 v94, vcc, s0, v102
	ds_read_b128 v[98:101], v108 offset:32
	s_nop 0
	v_addc_co_u32_e32 v95, vcc, 0, v103, vcc
	global_load_dwordx4 v[94:97], v[94:95], off
	s_waitcnt lgkmcnt(0)
; __device__ __forceinline__ unsigned short f2bf(float f) { return (unsigned short)(cvtpk(f, 0.f) & 0xffffu); }
; __device__ __forceinline__ int crow(int r, int hi) { return (r & 3) + 8 * (r >> 2) + 4 * hi; }
; __device__ void attn_phase(const Params& p, int l, int L, unsigned char* smem, int T) {
;     ...
;         for (int r4 = 0; r4 < 4; ++r4) { const f32x4 a0 = OS[r4 * 512], a1 = OS[(4 + r4) * 512], a2 = OS[(8 + r4) * 512], a3 = OS[(12 + r4) * 512];
; #pragma unroll
;           for (int q = 0; q < 4; ++q) { const int r = r4 * 4 + q; const int orow = crow(r, hi);
;             const float i2 = lam * __builtin_amdgcn_rcpf(li1[orow]);
;             const float v0 = a0[q] - o[0][r] * i2, v1 = a1[q] - o[1][r] * i2, v2 = a2[q] - o[2][r] * i2, v3 = a3[q] - o[3][r] * i2;
;             float ss = v0 * v0 + v1 * v1 + v2 * v2 + v3 * v3;
;             ss += __shfl_xor(ss, 1, 64); ss += __shfl_xor(ss, 2, 64); ss += __shfl_xor(ss, 4, 64); ss += __shfl_xor(ss, 8, 64); ss += __shfl_xor(ss, 16, 64);
;             const float rs = rsqrtf(ss * (1.f / 128.f) + EPS) * oml;
;             bf16_t* op = Ow + (size_t)orow * 1024;
;             op[0] = f2bf(v0 * rs * sw0); op[32] = f2bf(v1 * rs * sw1); op[64] = f2bf(v2 * rs * sw2); op[96] = f2bf(v3 * rs * sw3); } }
	v_rcp_f32_e32 v98, v98
	s_nop 0
	v_mul_f32_e32 v98, v167, v98
	s_waitcnt vmcnt(3)
	v_mov_b32_e32 v200, v86
	s_waitcnt vmcnt(2)
	v_mov_b32_e32 v201, v90
	v_pk_fma_f32 v[198:199], v[198:199], v[98:99], v[200:201] op_sel_hi:[1,0,1] neg_lo:[1,0,0] neg_hi:[1,0,0]
	v_mov_b32_e32 v90, v87
	v_pk_mul_f32 v[200:201], v[198:199], v[198:199]
	s_waitcnt vmcnt(1)
	v_mov_b32_e32 v205, v82
	v_rcp_f32_e32 v82, v99
	s_waitcnt vmcnt(0)
	v_mov_b32_e32 v204, v94
	v_pk_fma_f32 v[202:203], v[202:203], v[98:99], v[204:205] op_sel_hi:[1,0,1] neg_lo:[1,0,0] neg_hi:[1,0,0]
	v_mul_f32_e32 v86, v167, v82
	v_mov_b32_e32 v98, v55
	v_mov_b32_e32 v99, v39
	v_pk_fma_f32 v[90:91], v[98:99], v[86:87], v[90:91] op_sel_hi:[1,0,1] neg_lo:[1,0,0] neg_hi:[1,0,0]
	v_mov_b32_e32 v82, v95
	v_pk_mul_f32 v[98:99], v[90:91], v[90:91]
	v_pk_fma_f32 v[82:83], v[208:209], v[86:87], v[82:83] op_sel_hi:[1,0,1] neg_lo:[1,0,0] neg_hi:[1,0,0]
	v_pk_mul_f32 v[204:205], v[202:203], v[202:203]
	v_pk_mul_f32 v[86:87], v[82:83], v[82:83]
	v_mov_b32_e32 v94, v98
	v_mov_b32_e32 v95, v200
	v_mov_b32_e32 v200, v99
	v_pk_add_f32 v[94:95], v[94:95], v[200:201]
	v_mov_b32_e32 v98, v87
	v_mov_b32_e32 v99, v205
	v_pk_add_f32 v[94:95], v[98:99], v[94:95]
	v_mov_b32_e32 v87, v204
	v_pk_add_f32 v[86:87], v[86:87], v[94:95]
	ds_bpermute_b32 v95, v197, v87
	ds_bpermute_b32 v94, v197, v86
	v_mov_b32_e32 v99, v84
	v_rcp_f32_e32 v84, v101
	v_mov_b32_e32 v101, v41
	v_mov_b32_e32 v98, v96
	s_waitcnt lgkmcnt(0)
	v_pk_add_f32 v[86:87], v[86:87], v[94:95]
	ds_bpermute_b32 v95, v196, v87
	ds_bpermute_b32 v94, v196, v86
	v_mov_b32_e32 v208, v11
	v_mov_b32_e32 v209, v27
	s_waitcnt lgkmcnt(0)
	v_pk_add_f32 v[86:87], v[86:87], v[94:95]
	ds_bpermute_b32 v95, v195, v87
	ds_bpermute_b32 v94, v195, v86
	s_waitcnt lgkmcnt(0)
	v_pk_add_f32 v[86:87], v[86:87], v[94:95]
	ds_bpermute_b32 v95, v113, v87
	ds_bpermute_b32 v94, v113, v86
	s_waitcnt lgkmcnt(0)
	v_pk_add_f32 v[86:87], v[86:87], v[94:95]
	ds_bpermute_b32 v95, v0, v87
	ds_bpermute_b32 v94, v0, v86
	s_waitcnt lgkmcnt(0)
	v_pk_add_f32 v[86:87], v[86:87], v[94:95]
	s_nop 0
	v_pk_fma_f32 v[86:87], v[86:87], s[64:65], v[106:107] op_sel_hi:[1,0,0]
	v_mov_b32_e32 v95, v24
	v_mul_f32_e32 v94, 0x4b800000, v87
	v_cmp_gt_f32_e64 s[0:1], s63, v87
	v_cmp_gt_f32_e32 vcc, s63, v86
	s_nop 0
	v_cndmask_b32_e64 v87, v87, v94, s[0:1]
	v_rsq_f32_e32 v87, v87
	s_nop 0
	v_mul_f32_e32 v94, 0x45800000, v87
	v_cndmask_b32_e64 v87, v87, v94, s[0:1]
	v_mul_f32_e32 v87, v166, v87
	v_mul_f32_e32 v94, v198, v87
	v_mul_f32_e32 v94, v112, v94
	v_cvt_pk_bf16_f32 v94, v94, s0
	ds_write_b16 v220, v94 offset:2048
	v_mul_f32_e32 v94, v199, v87
	v_mul_f32_e32 v94, v111, v94
	v_cvt_pk_bf16_f32 v94, v94, s0
	ds_write_b16 v220, v94 offset:2112
	v_mul_f32_e32 v94, v203, v87
	v_mul_f32_e32 v87, v202, v87
	v_mul_f32_e32 v87, v109, v87
	v_cvt_pk_bf16_f32 v87, v87, s0
	ds_write_b16 v220, v87 offset:2240
	v_mul_f32_e32 v87, 0x4b800000, v86
	v_cndmask_b32_e32 v86, v86, v87, vcc
	v_rsq_f32_e32 v86, v86
	v_mul_f32_e32 v94, v110, v94
	v_cvt_pk_bf16_f32 v94, v94, s0
	ds_write_b16 v220, v94 offset:2176
	v_mul_f32_e32 v87, 0x45800000, v86
	v_cndmask_b32_e32 v86, v86, v87, vcc
	v_mul_f32_e32 v94, v166, v86
	v_mul_f32_e32 v82, v82, v94
	v_mul_f32_e32 v90, v90, v94
	v_mul_f32_e32 v82, v109, v82
	v_mul_f32_e32 v90, v112, v90
	v_cvt_pk_bf16_f32 v82, v82, s0
	v_cvt_pk_bf16_f32 v90, v90, s0
	ds_write_b16 v220, v82 offset:2496
	v_rcp_f32_e32 v82, v100
	ds_write_b16 v220, v90 offset:2304
	v_mul_f32_e32 v90, v91, v94
	v_mul_f32_e32 v83, v83, v94
	v_mul_f32_e32 v90, v111, v90
	v_mul_f32_e32 v83, v110, v83
	v_cvt_pk_bf16_f32 v90, v90, s0
	v_cvt_pk_bf16_f32 v83, v83, s0
	ds_write_b16 v220, v90 offset:2368
	ds_write_b16 v220, v83 offset:2432
	v_mul_f32_e32 v82, v167, v82
	v_mov_b32_e32 v86, v56
	v_mov_b32_e32 v87, v40
	v_mov_b32_e32 v90, v88
	v_mov_b32_e32 v91, v92
	v_mul_f32_e32 v88, v167, v84
	v_mov_b32_e32 v100, v57
	v_mov_b32_e32 v92, v89
	v_pk_fma_f32 v[86:87], v[86:87], v[82:83], v[90:91] op_sel_hi:[1,0,1] neg_lo:[1,0,0] neg_hi:[1,0,0]
	v_mov_b32_e32 v94, v8
	v_pk_fma_f32 v[92:93], v[100:101], v[88:89], v[92:93] op_sel_hi:[1,0,1] neg_lo:[1,0,0] neg_hi:[1,0,0]
	v_mov_b32_e32 v198, v9
	v_mov_b32_e32 v199, v25
	v_mov_b32_e32 v84, v97
	v_pk_mul_f32 v[90:91], v[86:87], v[86:87]
	v_pk_fma_f32 v[82:83], v[94:95], v[82:83], v[98:99] op_sel_hi:[1,0,1] neg_lo:[1,0,0] neg_hi:[1,0,0]
	v_pk_mul_f32 v[100:101], v[92:93], v[92:93]
	v_pk_fma_f32 v[84:85], v[198:199], v[88:89], v[84:85] op_sel_hi:[1,0,1] neg_lo:[1,0,0] neg_hi:[1,0,0]
	v_pk_mul_f32 v[94:95], v[82:83], v[82:83]
	v_pk_mul_f32 v[88:89], v[84:85], v[84:85]
	v_mov_b32_e32 v96, v100
	v_mov_b32_e32 v97, v90
	v_mov_b32_e32 v90, v101
	v_pk_add_f32 v[90:91], v[96:97], v[90:91]
	v_mov_b32_e32 v96, v89
	v_mov_b32_e32 v97, v95
	v_pk_add_f32 v[90:91], v[96:97], v[90:91]
	v_mov_b32_e32 v89, v94
	v_pk_add_f32 v[88:89], v[88:89], v[90:91]
	ds_bpermute_b32 v91, v197, v89
	ds_bpermute_b32 v90, v197, v88
	v_mov_b32_e32 v198, v58
	v_mov_b32_e32 v199, v42
	v_mov_b32_e32 v202, v10
	s_waitcnt lgkmcnt(0)
	v_pk_add_f32 v[88:89], v[88:89], v[90:91]
	ds_bpermute_b32 v91, v196, v89
	ds_bpermute_b32 v90, v196, v88
	v_mov_b32_e32 v203, v26
	s_waitcnt lgkmcnt(0)
	v_pk_add_f32 v[88:89], v[88:89], v[90:91]
	ds_bpermute_b32 v91, v195, v89
	ds_bpermute_b32 v90, v195, v88
	s_waitcnt lgkmcnt(0)
	v_pk_add_f32 v[88:89], v[88:89], v[90:91]
	ds_bpermute_b32 v91, v113, v89
	ds_bpermute_b32 v90, v113, v88
	s_waitcnt lgkmcnt(0)
	v_pk_add_f32 v[88:89], v[88:89], v[90:91]
	ds_bpermute_b32 v91, v0, v89
	ds_bpermute_b32 v90, v0, v88
	s_waitcnt lgkmcnt(0)
; __device__ __forceinline__ unsigned short f2bf(float f) { return (unsigned short)(cvtpk(f, 0.f) & 0xffffu); }
; __device__ __forceinline__ int crow(int r, int hi) { return (r & 3) + 8 * (r >> 2) + 4 * hi; }
; __device__ void attn_phase(const Params& p, int l, int L, unsigned char* smem, int T) {
;     ...
;         for (int r4 = 0; r4 < 4; ++r4) { const f32x4 a0 = OS[r4 * 512], a1 = OS[(4 + r4) * 512], a2 = OS[(8 + r4) * 512], a3 = OS[(12 + r4) * 512];
; #pragma unroll
;           for (int q = 0; q < 4; ++q) { const int r = r4 * 4 + q; const int orow = crow(r, hi);
;             const float i2 = lam * __builtin_amdgcn_rcpf(li1[orow]);
;             const float v0 = a0[q] - o[0][r] * i2, v1 = a1[q] - o[1][r] * i2, v2 = a2[q] - o[2][r] * i2, v3 = a3[q] - o[3][r] * i2;
;             float ss = v0 * v0 + v1 * v1 + v2 * v2 + v3 * v3;
;             ss += __shfl_xor(ss, 1, 64); ss += __shfl_xor(ss, 2, 64); ss += __shfl_xor(ss, 4, 64); ss += __shfl_xor(ss, 8, 64); ss += __shfl_xor(ss, 16, 64);
;             const float rs = rsqrtf(ss * (1.f / 128.f) + EPS) * oml;
;             bf16_t* op = Ow + (size_t)orow * 1024;
;             op[0] = f2bf(v0 * rs * sw0); op[32] = f2bf(v1 * rs * sw1); op[64] = f2bf(v2 * rs * sw2); op[96] = f2bf(v3 * rs * sw3); } }
	v_pk_add_f32 v[88:89], v[88:89], v[90:91]
	s_nop 0
	v_pk_fma_f32 v[88:89], v[88:89], s[64:65], v[106:107] op_sel_hi:[1,0,0]
	s_nop 0
	v_mul_f32_e32 v90, 0x4b800000, v89
	v_cmp_gt_f32_e64 s[0:1], s63, v89
	v_cmp_gt_f32_e32 vcc, s63, v88
	s_nop 0
	v_cndmask_b32_e64 v89, v89, v90, s[0:1]
	v_rsq_f32_e32 v89, v89
	s_nop 0
	v_mul_f32_e32 v90, 0x45800000, v89
	v_cndmask_b32_e64 v89, v89, v90, s[0:1]
	v_mul_f32_e32 v89, v166, v89
	v_mul_f32_e32 v82, v82, v89
	v_mul_f32_e32 v82, v109, v82
	v_cvt_pk_bf16_f32 v82, v82, s0
	ds_write_b16 v220, v82 offset:2752
	v_mul_f32_e32 v82, 0x4b800000, v88
	v_cndmask_b32_e32 v82, v88, v82, vcc
	v_mul_f32_e32 v86, v86, v89
	v_rsq_f32_e32 v82, v82
	v_mul_f32_e32 v86, v112, v86
	v_mul_f32_e32 v83, v83, v89
	v_cvt_pk_bf16_f32 v86, v86, s0
	v_mul_f32_e32 v83, v110, v83
	ds_write_b16 v220, v86 offset:2560
	v_mul_f32_e32 v86, v87, v89
	v_cvt_pk_bf16_f32 v83, v83, s0
	v_mul_f32_e32 v86, v111, v86
	ds_write_b16 v220, v83 offset:2688
	v_mul_f32_e32 v83, 0x45800000, v82
	v_cvt_pk_bf16_f32 v86, v86, s0
	v_cndmask_b32_e32 v82, v82, v83, vcc
	ds_write_b16 v220, v86 offset:2624
	v_mul_f32_e32 v86, v166, v82
	v_mul_f32_e32 v87, v92, v86
	v_mul_f32_e32 v87, v112, v87
	v_cvt_pk_bf16_f32 v87, v87, s0
	ds_write_b16 v220, v87 offset:2816
	v_mul_f32_e32 v87, v93, v86
	v_mul_f32_e32 v85, v85, v86
	v_mul_f32_e32 v84, v84, v86
	v_mul_f32_e32 v87, v111, v87
	v_mul_f32_e32 v85, v110, v85
	v_mul_f32_e32 v84, v109, v84
	v_cvt_pk_bf16_f32 v87, v87, s0
	v_cvt_pk_bf16_f32 v85, v85, s0
	v_cvt_pk_bf16_f32 v84, v84, s0
	ds_write_b16 v220, v87 offset:2880
	ds_write_b16 v220, v85 offset:2944
	ds_write_b16 v220, v84 offset:3008
	v_add_co_u32_e32 v82, vcc, s95, v102
	s_mov_b32 s0, 0xc000
	s_nop 0
	v_addc_co_u32_e32 v83, vcc, 0, v103, vcc
	v_add_co_u32_e32 v86, vcc, s0, v102
	s_mov_b32 s0, 0x14000
	s_nop 0
	v_addc_co_u32_e32 v87, vcc, 0, v103, vcc
	v_add_co_u32_e32 v90, vcc, s0, v102
	global_load_dwordx4 v[82:85], v[82:83], off
	s_nop 0
	v_addc_co_u32_e32 v91, vcc, 0, v103, vcc
	s_mov_b32 s0, 0x1c000
	v_add_co_u32_e32 v94, vcc, s0, v102
	global_load_dwordx4 v[86:89], v[86:87], off
	s_nop 0
	v_addc_co_u32_e32 v95, vcc, 0, v103, vcc
	global_load_dwordx4 v[90:93], v[90:91], off
	ds_read_b128 v[98:101], v108 offset:64
	global_load_dwordx4 v[94:97], v[94:95], off
	s_waitcnt lgkmcnt(0)
	v_rcp_f32_e32 v98, v98
	s_nop 0
	v_mul_f32_e32 v98, v167, v98
	s_waitcnt vmcnt(3)
	v_mov_b32_e32 v200, v82
	v_rcp_f32_e32 v82, v99
	s_waitcnt vmcnt(2)
	v_mov_b32_e32 v201, v86
	v_pk_fma_f32 v[198:199], v[198:199], v[98:99], v[200:201] op_sel_hi:[1,0,1] neg_lo:[1,0,0] neg_hi:[1,0,0]
	v_mul_f32_e32 v82, v167, v82
	s_waitcnt vmcnt(1)
	v_mov_b32_e32 v205, v90
	v_mov_b32_e32 v86, v83
	s_waitcnt vmcnt(0)
	v_mov_b32_e32 v204, v94
	v_pk_fma_f32 v[202:203], v[202:203], v[98:99], v[204:205] op_sel_hi:[1,0,1] neg_lo:[1,0,0] neg_hi:[1,0,0]
	v_mov_b32_e32 v98, v59
	v_mov_b32_e32 v99, v43
	v_pk_fma_f32 v[86:87], v[98:99], v[82:83], v[86:87] op_sel_hi:[1,0,1] neg_lo:[1,0,0] neg_hi:[1,0,0]
	v_mov_b32_e32 v90, v95
	v_pk_mul_f32 v[200:201], v[198:199], v[198:199]
	v_pk_mul_f32 v[98:99], v[86:87], v[86:87]
	v_pk_fma_f32 v[82:83], v[208:209], v[82:83], v[90:91] op_sel_hi:[1,0,1] neg_lo:[1,0,0] neg_hi:[1,0,0]
	v_pk_mul_f32 v[204:205], v[202:203], v[202:203]
	v_pk_mul_f32 v[90:91], v[82:83], v[82:83]
	v_mov_b32_e32 v94, v98
	v_mov_b32_e32 v95, v200
	v_mov_b32_e32 v200, v99
	v_pk_add_f32 v[94:95], v[94:95], v[200:201]
	v_mov_b32_e32 v98, v91
	v_mov_b32_e32 v99, v205
	v_pk_add_f32 v[94:95], v[98:99], v[94:95]
	v_mov_b32_e32 v91, v204
	v_pk_add_f32 v[90:91], v[90:91], v[94:95]
	ds_bpermute_b32 v95, v197, v91
	ds_bpermute_b32 v94, v197, v90
	v_mov_b32_e32 v98, v96
	v_mov_b32_e32 v99, v92
	v_mov_b32_e32 v92, v97
	v_mov_b32_e32 v208, v15
	s_waitcnt lgkmcnt(0)
	v_pk_add_f32 v[90:91], v[90:91], v[94:95]
	ds_bpermute_b32 v95, v196, v91
	ds_bpermute_b32 v94, v196, v90
	v_mov_b32_e32 v209, v31
	s_waitcnt lgkmcnt(0)
	v_pk_add_f32 v[90:91], v[90:91], v[94:95]
	ds_bpermute_b32 v95, v195, v91
	ds_bpermute_b32 v94, v195, v90
	s_waitcnt lgkmcnt(0)
	v_pk_add_f32 v[90:91], v[90:91], v[94:95]
	ds_bpermute_b32 v95, v113, v91
	ds_bpermute_b32 v94, v113, v90
	s_waitcnt lgkmcnt(0)
	v_pk_add_f32 v[90:91], v[90:91], v[94:95]
	ds_bpermute_b32 v95, v0, v91
	ds_bpermute_b32 v94, v0, v90
	s_waitcnt lgkmcnt(0)
; __device__ __forceinline__ unsigned short f2bf(float f) { return (unsigned short)(cvtpk(f, 0.f) & 0xffffu); }
; __device__ __forceinline__ int crow(int r, int hi) { return (r & 3) + 8 * (r >> 2) + 4 * hi; }
; __device__ void attn_phase(const Params& p, int l, int L, unsigned char* smem, int T) {
;     ...
;         for (int r4 = 0; r4 < 4; ++r4) { const f32x4 a0 = OS[r4 * 512], a1 = OS[(4 + r4) * 512], a2 = OS[(8 + r4) * 512], a3 = OS[(12 + r4) * 512];
; #pragma unroll
;           for (int q = 0; q < 4; ++q) { const int r = r4 * 4 + q; const int orow = crow(r, hi);
;             const float i2 = lam * __builtin_amdgcn_rcpf(li1[orow]);
;             const float v0 = a0[q] - o[0][r] * i2, v1 = a1[q] - o[1][r] * i2, v2 = a2[q] - o[2][r] * i2, v3 = a3[q] - o[3][r] * i2;
;             float ss = v0 * v0 + v1 * v1 + v2 * v2 + v3 * v3;
;             ss += __shfl_xor(ss, 1, 64); ss += __shfl_xor(ss, 2, 64); ss += __shfl_xor(ss, 4, 64); ss += __shfl_xor(ss, 8, 64); ss += __shfl_xor(ss, 16, 64);
;             const float rs = rsqrtf(ss * (1.f / 128.f) + EPS) * oml;
;             bf16_t* op = Ow + (size_t)orow * 1024;
;             op[0] = f2bf(v0 * rs * sw0); op[32] = f2bf(v1 * rs * sw1); op[64] = f2bf(v2 * rs * sw2); op[96] = f2bf(v3 * rs * sw3); } }
	v_pk_add_f32 v[90:91], v[90:91], v[94:95]
	s_nop 0
	v_pk_fma_f32 v[90:91], v[90:91], s[64:65], v[106:107] op_sel_hi:[1,0,0]
	v_mov_b32_e32 v95, v28
	v_mul_f32_e32 v94, 0x4b800000, v91
	v_cmp_gt_f32_e64 s[0:1], s63, v91
	v_cmp_gt_f32_e32 vcc, s63, v90
	s_nop 0
	v_cndmask_b32_e64 v91, v91, v94, s[0:1]
	v_rsq_f32_e32 v91, v91
	s_nop 0
	v_mul_f32_e32 v94, 0x45800000, v91
	v_cndmask_b32_e64 v91, v91, v94, s[0:1]
	v_mul_f32_e32 v91, v166, v91
	v_mul_f32_e32 v94, v198, v91
	v_mul_f32_e32 v94, v112, v94
	v_cvt_pk_bf16_f32 v94, v94, s0
	ds_write_b16 v220, v94 offset:4096
	v_mul_f32_e32 v94, v199, v91
	v_mul_f32_e32 v94, v111, v94
	v_cvt_pk_bf16_f32 v94, v94, s0
	ds_write_b16 v220, v94 offset:4160
	v_mul_f32_e32 v94, v203, v91
	v_mul_f32_e32 v91, v202, v91
	v_mul_f32_e32 v91, v109, v91
	v_cvt_pk_bf16_f32 v91, v91, s0
	ds_write_b16 v220, v91 offset:4288
	v_mul_f32_e32 v91, 0x4b800000, v90
	v_cndmask_b32_e32 v90, v90, v91, vcc
	v_rsq_f32_e32 v90, v90
	v_mul_f32_e32 v94, v110, v94
	v_cvt_pk_bf16_f32 v94, v94, s0
	ds_write_b16 v220, v94 offset:4224
	v_mul_f32_e32 v91, 0x45800000, v90
	v_cndmask_b32_e32 v90, v90, v91, vcc
	v_mul_f32_e32 v94, v166, v90
	v_mul_f32_e32 v86, v86, v94
	v_mul_f32_e32 v86, v112, v86
	v_cvt_pk_bf16_f32 v86, v86, s0
	ds_write_b16 v220, v86 offset:4352
	v_mul_f32_e32 v86, v87, v94
	v_mul_f32_e32 v83, v83, v94
	v_mul_f32_e32 v82, v82, v94
	v_mul_f32_e32 v86, v111, v86
	v_mul_f32_e32 v83, v110, v83
	v_mul_f32_e32 v82, v109, v82
	v_cvt_pk_bf16_f32 v86, v86, s0
	v_cvt_pk_bf16_f32 v83, v83, s0
	v_cvt_pk_bf16_f32 v82, v82, s0
	ds_write_b16 v220, v86 offset:4416
	ds_write_b16 v220, v83 offset:4480
	ds_write_b16 v220, v82 offset:4544
	v_rcp_f32_e32 v82, v100
	v_mov_b32_e32 v90, v84
	v_rcp_f32_e32 v84, v101
	v_mov_b32_e32 v86, v60
	v_mul_f32_e32 v82, v167, v82
	v_mov_b32_e32 v87, v44
	v_mov_b32_e32 v91, v88
	v_mul_f32_e32 v84, v167, v84
	v_mov_b32_e32 v100, v61
	v_mov_b32_e32 v101, v45
	v_mov_b32_e32 v88, v85
	v_pk_fma_f32 v[86:87], v[86:87], v[82:83], v[90:91] op_sel_hi:[1,0,1] neg_lo:[1,0,0] neg_hi:[1,0,0]
	v_mov_b32_e32 v94, v12
	v_pk_fma_f32 v[88:89], v[100:101], v[84:85], v[88:89] op_sel_hi:[1,0,1] neg_lo:[1,0,0] neg_hi:[1,0,0]
	v_mov_b32_e32 v198, v13
	v_mov_b32_e32 v199, v29
	v_pk_mul_f32 v[90:91], v[86:87], v[86:87]
	v_pk_fma_f32 v[82:83], v[94:95], v[82:83], v[98:99] op_sel_hi:[1,0,1] neg_lo:[1,0,0] neg_hi:[1,0,0]
	v_pk_mul_f32 v[100:101], v[88:89], v[88:89]
	v_pk_fma_f32 v[84:85], v[198:199], v[84:85], v[92:93] op_sel_hi:[1,0,1] neg_lo:[1,0,0] neg_hi:[1,0,0]
	v_pk_mul_f32 v[94:95], v[82:83], v[82:83]
	v_pk_mul_f32 v[92:93], v[84:85], v[84:85]
	v_mov_b32_e32 v96, v100
	v_mov_b32_e32 v97, v90
	v_mov_b32_e32 v90, v101
	v_pk_add_f32 v[90:91], v[96:97], v[90:91]
	v_mov_b32_e32 v96, v93
	v_mov_b32_e32 v97, v95
	v_pk_add_f32 v[90:91], v[96:97], v[90:91]
	v_mov_b32_e32 v93, v94
	v_pk_add_f32 v[90:91], v[92:93], v[90:91]
	ds_bpermute_b32 v93, v197, v91
	ds_bpermute_b32 v92, v197, v90
	v_mov_b32_e32 v198, v62
	v_mov_b32_e32 v199, v46
	v_mov_b32_e32 v202, v14
	s_waitcnt lgkmcnt(0)
	v_pk_add_f32 v[90:91], v[90:91], v[92:93]
	ds_bpermute_b32 v93, v196, v91
	ds_bpermute_b32 v92, v196, v90
	v_mov_b32_e32 v203, v30
	s_waitcnt lgkmcnt(0)
	v_pk_add_f32 v[90:91], v[90:91], v[92:93]
	ds_bpermute_b32 v93, v195, v91
	ds_bpermute_b32 v92, v195, v90
	s_waitcnt lgkmcnt(0)
	v_pk_add_f32 v[90:91], v[90:91], v[92:93]
	ds_bpermute_b32 v93, v113, v91
	ds_bpermute_b32 v92, v113, v90
	s_waitcnt lgkmcnt(0)
	v_pk_add_f32 v[90:91], v[90:91], v[92:93]
	ds_bpermute_b32 v93, v0, v91
	ds_bpermute_b32 v92, v0, v90
	s_waitcnt lgkmcnt(0)
	v_pk_add_f32 v[90:91], v[90:91], v[92:93]
	s_nop 0
	v_pk_fma_f32 v[90:91], v[90:91], s[64:65], v[106:107] op_sel_hi:[1,0,0]
	s_nop 0
	v_mul_f32_e32 v92, 0x4b800000, v91
	v_cmp_gt_f32_e64 s[0:1], s63, v91
	v_cmp_gt_f32_e32 vcc, s63, v90
	s_nop 0
	v_cndmask_b32_e64 v91, v91, v92, s[0:1]
	v_rsq_f32_e32 v91, v91
	s_nop 0
	v_mul_f32_e32 v92, 0x45800000, v91
	v_cndmask_b32_e64 v91, v91, v92, s[0:1]
	v_mul_f32_e32 v91, v166, v91
	v_mul_f32_e32 v82, v82, v91
	v_mul_f32_e32 v82, v109, v82
	v_cvt_pk_bf16_f32 v82, v82, s0
	ds_write_b16 v220, v82 offset:4800
	v_mul_f32_e32 v82, 0x4b800000, v90
	v_cndmask_b32_e32 v82, v90, v82, vcc
	v_mul_f32_e32 v86, v86, v91
	v_rsq_f32_e32 v82, v82
	v_mul_f32_e32 v86, v112, v86
	v_mul_f32_e32 v83, v83, v91
	v_cvt_pk_bf16_f32 v86, v86, s0
	v_mul_f32_e32 v83, v110, v83
	ds_write_b16 v220, v86 offset:4608
	v_mul_f32_e32 v86, v87, v91
	v_cvt_pk_bf16_f32 v83, v83, s0
	v_mul_f32_e32 v86, v111, v86
	ds_write_b16 v220, v83 offset:4736
	v_mul_f32_e32 v83, 0x45800000, v82
	v_cvt_pk_bf16_f32 v86, v86, s0
	v_cndmask_b32_e32 v82, v82, v83, vcc
	ds_write_b16 v220, v86 offset:4672
	v_mul_f32_e32 v86, v166, v82
	v_mul_f32_e32 v87, v88, v86
	v_mul_f32_e32 v87, v112, v87
	v_cvt_pk_bf16_f32 v87, v87, s0
	ds_write_b16 v220, v87 offset:4864
	v_mul_f32_e32 v87, v89, v86
	v_mul_f32_e32 v85, v85, v86
	v_mul_f32_e32 v84, v84, v86
	v_mul_f32_e32 v87, v111, v87
	v_mul_f32_e32 v85, v110, v85
	v_mul_f32_e32 v84, v109, v84
	v_cvt_pk_bf16_f32 v87, v87, s0
	v_cvt_pk_bf16_f32 v85, v85, s0
	v_cvt_pk_bf16_f32 v84, v84, s0
	ds_write_b16 v220, v87 offset:4928
	ds_write_b16 v220, v85 offset:4992
	ds_write_b16 v220, v84 offset:5056
	v_add_co_u32_e32 v82, vcc, s87, v102
	s_mov_b32 s0, 0xe000
	s_nop 0
	v_addc_co_u32_e32 v83, vcc, 0, v103, vcc
	global_load_dwordx4 v[86:89], v[82:83], off
	v_add_co_u32_e32 v82, vcc, s0, v102
	s_mov_b32 s0, 0x16000
	s_nop 0
	v_addc_co_u32_e32 v83, vcc, 0, v103, vcc
	global_load_dwordx4 v[90:93], v[82:83], off
	v_add_co_u32_e32 v82, vcc, s0, v102
	s_mov_b32 s0, 0x1e000
	s_nop 0
	v_addc_co_u32_e32 v83, vcc, 0, v103, vcc
	global_load_dwordx4 v[82:85], v[82:83], off
	v_add_co_u32_e32 v94, vcc, s0, v102
	ds_read_b128 v[98:101], v108 offset:96
	s_nop 0
	v_addc_co_u32_e32 v95, vcc, 0, v103, vcc
	global_load_dwordx4 v[94:97], v[94:95], off
	s_waitcnt lgkmcnt(0)
; __device__ __forceinline__ unsigned short f2bf(float f) { return (unsigned short)(cvtpk(f, 0.f) & 0xffffu); }
; __device__ __forceinline__ int crow(int r, int hi) { return (r & 3) + 8 * (r >> 2) + 4 * hi; }
; __device__ void attn_phase(const Params& p, int l, int L, unsigned char* smem, int T) {
;     ...
;         for (int r4 = 0; r4 < 4; ++r4) { const f32x4 a0 = OS[r4 * 512], a1 = OS[(4 + r4) * 512], a2 = OS[(8 + r4) * 512], a3 = OS[(12 + r4) * 512];
; #pragma unroll
;           for (int q = 0; q < 4; ++q) { const int r = r4 * 4 + q; const int orow = crow(r, hi);
;             const float i2 = lam * __builtin_amdgcn_rcpf(li1[orow]);
;             const float v0 = a0[q] - o[0][r] * i2, v1 = a1[q] - o[1][r] * i2, v2 = a2[q] - o[2][r] * i2, v3 = a3[q] - o[3][r] * i2;
;             float ss = v0 * v0 + v1 * v1 + v2 * v2 + v3 * v3;
;             ss += __shfl_xor(ss, 1, 64); ss += __shfl_xor(ss, 2, 64); ss += __shfl_xor(ss, 4, 64); ss += __shfl_xor(ss, 8, 64); ss += __shfl_xor(ss, 16, 64);
;             const float rs = rsqrtf(ss * (1.f / 128.f) + EPS) * oml;
;             bf16_t* op = Ow + (size_t)orow * 1024;
;             op[0] = f2bf(v0 * rs * sw0); op[32] = f2bf(v1 * rs * sw1); op[64] = f2bf(v2 * rs * sw2); op[96] = f2bf(v3 * rs * sw3); } }
	v_rcp_f32_e32 v98, v98
	s_nop 0
	v_mul_f32_e32 v98, v167, v98
	s_waitcnt vmcnt(3)
	v_mov_b32_e32 v200, v86
	s_waitcnt vmcnt(2)
	v_mov_b32_e32 v201, v90
	v_pk_fma_f32 v[198:199], v[198:199], v[98:99], v[200:201] op_sel_hi:[1,0,1] neg_lo:[1,0,0] neg_hi:[1,0,0]
	v_mov_b32_e32 v90, v87
	v_pk_mul_f32 v[200:201], v[198:199], v[198:199]
	s_waitcnt vmcnt(1)
	v_mov_b32_e32 v205, v82
	v_rcp_f32_e32 v82, v99
	s_waitcnt vmcnt(0)
	v_mov_b32_e32 v204, v94
	v_pk_fma_f32 v[202:203], v[202:203], v[98:99], v[204:205] op_sel_hi:[1,0,1] neg_lo:[1,0,0] neg_hi:[1,0,0]
	v_mul_f32_e32 v86, v167, v82
	v_mov_b32_e32 v98, v63
	v_mov_b32_e32 v99, v47
	v_pk_fma_f32 v[90:91], v[98:99], v[86:87], v[90:91] op_sel_hi:[1,0,1] neg_lo:[1,0,0] neg_hi:[1,0,0]
	v_mov_b32_e32 v82, v95
	v_pk_mul_f32 v[98:99], v[90:91], v[90:91]
	v_pk_fma_f32 v[82:83], v[208:209], v[86:87], v[82:83] op_sel_hi:[1,0,1] neg_lo:[1,0,0] neg_hi:[1,0,0]
	v_pk_mul_f32 v[204:205], v[202:203], v[202:203]
	v_pk_mul_f32 v[86:87], v[82:83], v[82:83]
	v_mov_b32_e32 v94, v98
	v_mov_b32_e32 v95, v200
	v_mov_b32_e32 v200, v99
	v_pk_add_f32 v[94:95], v[94:95], v[200:201]
	v_mov_b32_e32 v98, v87
	v_mov_b32_e32 v99, v205
	v_pk_add_f32 v[94:95], v[98:99], v[94:95]
	v_mov_b32_e32 v87, v204
	v_pk_add_f32 v[86:87], v[86:87], v[94:95]
	ds_bpermute_b32 v95, v197, v87
	ds_bpermute_b32 v94, v197, v86
	v_mov_b32_e32 v99, v84
	v_rcp_f32_e32 v84, v101
	v_mov_b32_e32 v101, v49
	v_mov_b32_e32 v98, v96
	s_waitcnt lgkmcnt(0)
	v_pk_add_f32 v[86:87], v[86:87], v[94:95]
	ds_bpermute_b32 v95, v196, v87
	ds_bpermute_b32 v94, v196, v86
	s_waitcnt lgkmcnt(0)
	v_pk_add_f32 v[86:87], v[86:87], v[94:95]
	ds_bpermute_b32 v95, v195, v87
	ds_bpermute_b32 v94, v195, v86
	s_waitcnt lgkmcnt(0)
	v_pk_add_f32 v[86:87], v[86:87], v[94:95]
	ds_bpermute_b32 v95, v113, v87
	ds_bpermute_b32 v94, v113, v86
	s_waitcnt lgkmcnt(0)
	v_pk_add_f32 v[86:87], v[86:87], v[94:95]
	ds_bpermute_b32 v95, v0, v87
	ds_bpermute_b32 v94, v0, v86
	s_waitcnt lgkmcnt(0)
	v_pk_add_f32 v[86:87], v[86:87], v[94:95]
	s_nop 0
	v_pk_fma_f32 v[86:87], v[86:87], s[64:65], v[106:107] op_sel_hi:[1,0,0]
	v_mov_b32_e32 v95, v32
	v_mul_f32_e32 v94, 0x4b800000, v87
	v_cmp_gt_f32_e64 s[0:1], s63, v87
	v_cmp_gt_f32_e32 vcc, s63, v86
	s_nop 0
	v_cndmask_b32_e64 v87, v87, v94, s[0:1]
	v_rsq_f32_e32 v87, v87
	s_nop 0
	v_mul_f32_e32 v94, 0x45800000, v87
	v_cndmask_b32_e64 v87, v87, v94, s[0:1]
	v_mul_f32_e32 v87, v166, v87
	v_mul_f32_e32 v94, v198, v87
	v_mul_f32_e32 v94, v112, v94
	v_cvt_pk_bf16_f32 v94, v94, s0
	ds_write_b16 v220, v94 offset:6144
	v_mul_f32_e32 v94, v199, v87
	v_mul_f32_e32 v94, v111, v94
	v_cvt_pk_bf16_f32 v94, v94, s0
	ds_write_b16 v220, v94 offset:6208
	v_mul_f32_e32 v94, v203, v87
	v_mul_f32_e32 v87, v202, v87
	v_mul_f32_e32 v87, v109, v87
	v_cvt_pk_bf16_f32 v87, v87, s0
	ds_write_b16 v220, v87 offset:6336
	v_mul_f32_e32 v87, 0x4b800000, v86
	v_cndmask_b32_e32 v86, v86, v87, vcc
	v_rsq_f32_e32 v86, v86
	v_mul_f32_e32 v94, v110, v94
	v_cvt_pk_bf16_f32 v94, v94, s0
	ds_write_b16 v220, v94 offset:6272
	v_mul_f32_e32 v87, 0x45800000, v86
	v_cndmask_b32_e32 v86, v86, v87, vcc
	v_mul_f32_e32 v94, v166, v86
	v_mul_f32_e32 v82, v82, v94
	v_mul_f32_e32 v90, v90, v94
	v_mul_f32_e32 v82, v109, v82
	v_mul_f32_e32 v90, v112, v90
	v_cvt_pk_bf16_f32 v82, v82, s0
	v_cvt_pk_bf16_f32 v90, v90, s0
	ds_write_b16 v220, v82 offset:6592
	v_rcp_f32_e32 v82, v100
	ds_write_b16 v220, v90 offset:6400
	v_mul_f32_e32 v90, v91, v94
	v_mul_f32_e32 v83, v83, v94
	v_mul_f32_e32 v90, v111, v90
	v_mul_f32_e32 v83, v110, v83
	v_cvt_pk_bf16_f32 v90, v90, s0
	v_cvt_pk_bf16_f32 v83, v83, s0
	ds_write_b16 v220, v90 offset:6464
	ds_write_b16 v220, v83 offset:6528
	v_mul_f32_e32 v82, v167, v82
	v_mov_b32_e32 v86, v64
	v_mov_b32_e32 v87, v48
	v_mov_b32_e32 v90, v88
	v_mov_b32_e32 v91, v92
	v_mul_f32_e32 v88, v167, v84
	v_mov_b32_e32 v100, v65
	v_mov_b32_e32 v92, v89
	v_pk_fma_f32 v[86:87], v[86:87], v[82:83], v[90:91] op_sel_hi:[1,0,1] neg_lo:[1,0,0] neg_hi:[1,0,0]
	v_mov_b32_e32 v94, v16
	v_pk_fma_f32 v[92:93], v[100:101], v[88:89], v[92:93] op_sel_hi:[1,0,1] neg_lo:[1,0,0] neg_hi:[1,0,0]
	v_mov_b32_e32 v198, v17
	v_mov_b32_e32 v199, v33
	v_mov_b32_e32 v84, v97
	v_pk_mul_f32 v[90:91], v[86:87], v[86:87]
	v_pk_fma_f32 v[82:83], v[94:95], v[82:83], v[98:99] op_sel_hi:[1,0,1] neg_lo:[1,0,0] neg_hi:[1,0,0]
	v_pk_mul_f32 v[100:101], v[92:93], v[92:93]
	v_pk_fma_f32 v[84:85], v[198:199], v[88:89], v[84:85] op_sel_hi:[1,0,1] neg_lo:[1,0,0] neg_hi:[1,0,0]
	v_pk_mul_f32 v[94:95], v[82:83], v[82:83]
	v_pk_mul_f32 v[88:89], v[84:85], v[84:85]
	v_mov_b32_e32 v96, v100
	v_mov_b32_e32 v97, v90
	v_mov_b32_e32 v90, v101
	v_pk_add_f32 v[90:91], v[96:97], v[90:91]
	v_mov_b32_e32 v96, v89
	v_mov_b32_e32 v97, v95
	v_pk_add_f32 v[90:91], v[96:97], v[90:91]
	v_mov_b32_e32 v89, v94
	v_pk_add_f32 v[88:89], v[88:89], v[90:91]
	ds_bpermute_b32 v91, v197, v89
	ds_bpermute_b32 v90, v197, v88
	s_waitcnt lgkmcnt(0)
; __device__ __forceinline__ unsigned short f2bf(float f) { return (unsigned short)(cvtpk(f, 0.f) & 0xffffu); }
; __device__ __forceinline__ int crow(int r, int hi) { return (r & 3) + 8 * (r >> 2) + 4 * hi; }
; __device__ void attn_phase(const Params& p, int l, int L, unsigned char* smem, int T) {
;     ...
;         for (int r4 = 0; r4 < 4; ++r4) { const f32x4 a0 = OS[r4 * 512], a1 = OS[(4 + r4) * 512], a2 = OS[(8 + r4) * 512], a3 = OS[(12 + r4) * 512];
; #pragma unroll
;           for (int q = 0; q < 4; ++q) { const int r = r4 * 4 + q; const int orow = crow(r, hi);
;             const float i2 = lam * __builtin_amdgcn_rcpf(li1[orow]);
;             const float v0 = a0[q] - o[0][r] * i2, v1 = a1[q] - o[1][r] * i2, v2 = a2[q] - o[2][r] * i2, v3 = a3[q] - o[3][r] * i2;
;             float ss = v0 * v0 + v1 * v1 + v2 * v2 + v3 * v3;
;             ss += __shfl_xor(ss, 1, 64); ss += __shfl_xor(ss, 2, 64); ss += __shfl_xor(ss, 4, 64); ss += __shfl_xor(ss, 8, 64); ss += __shfl_xor(ss, 16, 64);
;             const float rs = rsqrtf(ss * (1.f / 128.f) + EPS) * oml;
;             bf16_t* op = Ow + (size_t)orow * 1024;
;             op[0] = f2bf(v0 * rs * sw0); op[32] = f2bf(v1 * rs * sw1); op[64] = f2bf(v2 * rs * sw2); op[96] = f2bf(v3 * rs * sw3); } }
	v_pk_add_f32 v[88:89], v[88:89], v[90:91]
	ds_bpermute_b32 v91, v196, v89
	ds_bpermute_b32 v90, v196, v88
	s_waitcnt lgkmcnt(0)
	v_pk_add_f32 v[88:89], v[88:89], v[90:91]
	ds_bpermute_b32 v91, v195, v89
	ds_bpermute_b32 v90, v195, v88
	s_waitcnt lgkmcnt(0)
	v_pk_add_f32 v[88:89], v[88:89], v[90:91]
	ds_bpermute_b32 v91, v113, v89
	ds_bpermute_b32 v90, v113, v88
	s_waitcnt lgkmcnt(0)
	v_pk_add_f32 v[88:89], v[88:89], v[90:91]
	ds_bpermute_b32 v91, v0, v89
	ds_bpermute_b32 v90, v0, v88
	s_waitcnt lgkmcnt(0)
	v_pk_add_f32 v[88:89], v[88:89], v[90:91]
	s_nop 0
	v_pk_fma_f32 v[88:89], v[88:89], s[64:65], v[106:107] op_sel_hi:[1,0,0]
	s_nop 0
	v_mul_f32_e32 v0, 0x4b800000, v89
	v_cmp_gt_f32_e64 s[0:1], s63, v89
	v_cmp_gt_f32_e32 vcc, s63, v88
	s_nop 0
	v_cndmask_b32_e64 v0, v89, v0, s[0:1]
	v_rsq_f32_e32 v0, v0
	s_nop 0
	v_mul_f32_e32 v89, 0x45800000, v0
	v_cndmask_b32_e64 v0, v0, v89, s[0:1]
	v_mul_f32_e32 v0, v166, v0
	v_mul_f32_e32 v86, v86, v0
	v_mul_f32_e32 v86, v112, v86
	v_cvt_pk_bf16_f32 v86, v86, s0
	ds_write_b16 v220, v86 offset:6656
	v_mul_f32_e32 v86, v87, v0
	v_mul_f32_e32 v83, v83, v0
	v_mul_f32_e32 v0, v82, v0
	v_mul_f32_e32 v0, v109, v0
	v_cvt_pk_bf16_f32 v0, v0, s0
	ds_write_b16 v220, v0 offset:6848
	v_mul_f32_e32 v0, 0x4b800000, v88
	v_cndmask_b32_e32 v0, v88, v0, vcc
	v_rsq_f32_e32 v0, v0
	v_mul_f32_e32 v86, v111, v86
	v_cvt_pk_bf16_f32 v86, v86, s0
	ds_write_b16 v220, v86 offset:6720
	v_mul_f32_e32 v82, 0x45800000, v0
	v_cndmask_b32_e32 v0, v0, v82, vcc
	v_mul_f32_e32 v0, v166, v0
	v_mul_f32_e32 v83, v110, v83
	v_mul_f32_e32 v86, v92, v0
	v_cvt_pk_bf16_f32 v83, v83, s0
	v_mul_f32_e32 v86, v112, v86
	ds_write_b16 v220, v83 offset:6784
	v_cvt_pk_bf16_f32 v86, v86, s0
	ds_write_b16 v220, v86 offset:6912
	v_mul_f32_e32 v86, v93, v0
	v_mul_f32_e32 v85, v85, v0
	v_mul_f32_e32 v0, v84, v0
	v_mul_f32_e32 v86, v111, v86
	v_mul_f32_e32 v85, v110, v85
	v_mul_f32_e32 v0, v109, v0
	v_cvt_pk_bf16_f32 v86, v86, s0
	v_cvt_pk_bf16_f32 v85, v85, s0
	v_cvt_pk_bf16_f32 v0, v0, s0
	ds_write_b16 v220, v86 offset:6976
	ds_write_b16 v220, v85 offset:7040
	ds_write_b16 v220, v0 offset:7104
	s_waitcnt lgkmcnt(0)
	ds_read_b128 v[228:231], v226
	ds_read_b128 v[232:235], v226 offset:1024
	ds_read_b128 v[236:239], v226 offset:2048
	ds_read_b128 v[240:243], v226 offset:3072
	s_waitcnt lgkmcnt(3)
	global_store_dwordx4 v[244:245], v[228:231], off
	v_lshl_add_u64 v[244:245], v[244:245], 0, v[246:247]
	s_waitcnt lgkmcnt(2)
	global_store_dwordx4 v[244:245], v[232:235], off
	v_lshl_add_u64 v[244:245], v[244:245], 0, v[246:247]
	s_waitcnt lgkmcnt(1)
	global_store_dwordx4 v[244:245], v[236:239], off
	v_lshl_add_u64 v[244:245], v[244:245], 0, v[246:247]
	s_waitcnt lgkmcnt(0)
	global_store_dwordx4 v[244:245], v[240:243], off
	v_lshl_add_u64 v[244:245], v[244:245], 0, v[246:247]
	s_nop 1
	ds_read_b128 v[228:231], v226 offset:4096
	ds_read_b128 v[232:235], v226 offset:5120
	ds_read_b128 v[236:239], v226 offset:6144
	ds_read_b128 v[240:243], v226 offset:7168
	s_waitcnt lgkmcnt(3)
	global_store_dwordx4 v[244:245], v[228:231], off
	v_lshl_add_u64 v[244:245], v[244:245], 0, v[246:247]
	s_waitcnt lgkmcnt(2)
	global_store_dwordx4 v[244:245], v[232:235], off
	v_lshl_add_u64 v[244:245], v[244:245], 0, v[246:247]
	s_waitcnt lgkmcnt(1)
	global_store_dwordx4 v[244:245], v[236:239], off
	v_lshl_add_u64 v[244:245], v[244:245], 0, v[246:247]
	s_waitcnt lgkmcnt(0)
	global_store_dwordx4 v[244:245], v[240:243], off
	v_lshl_add_u64 v[244:245], v[244:245], 0, v[246:247]
	s_cbranch_execnz .LBB0_175
